# step 1: the 8 leftover layer-0 conversion tile units go to adaLN-GEMM workgroups 0-7 after their tile (converters do exactly 7 trips); on top of the idle-slot layer-1 conversion schedule
# speedup vs baseline: 1.0063x; 1.0063x over previous
; __device__ __forceinline__ void convert_layer(PP P, int l, LAS unsigned char* lds, const Ids I) {
;     ...
;     for (int u = BID; u < 7 * 176 + 64; u += NB) {
;         const int mi = u / 176, uu = u - mi * 176;
;         if (mi == 0)      conv_tile4(P->in[I_F1G] + wl, 1024, 2816, (bf16_t*)(ws + WS_WGU1), 5, uu, T, I);
;         else if (mi == 1) conv_tile4(P->in[I_F1U] + wl, 1024, 2816, (bf16_t*)(ws + WS_WGU1), 6, uu, T, I);
;         else if (mi == 2) conv_tile4(P->in[I_F1D] + wl, 2816, 1024, (bf16_t*)(ws + WS_WD1), 0, uu, T, I);
;         else if (mi == 3) conv_tile4(P->in[I_WIN] + wl, 1024, 2816, (bf16_t*)(ws + WS_WIN), 4, uu, T, I);
;         else if (mi == 4) conv_tile4(P->in[I_F2G] + wl, 1024, 2816, (bf16_t*)(ws + WS_WGU2), 5, uu, T, I);
;         else if (mi == 5) conv_tile4(P->in[I_F2U] + wl, 1024, 2816, (bf16_t*)(ws + WS_WGU2), 6, uu, T, I);
;         else if (mi == 6) conv_tile4(P->in[I_F2D] + wl, 2816, 1024, (bf16_t*)(ws + WS_WD2), 0, uu, T, I);
;         else              conv_tile4(P->in[I_WOUT] + (size_t)l * 1024 * 1024, 1024, 1024, (bf16_t*)(ws + WS_WOUT), 0, uu, T, I);
;     }
.LBB0_658:
	s_add_i32 s16, s17, s16
	s_add_i32 s18, s18, s17
	s_cmpk_gt_i32 s16, 0x507
	s_waitcnt lgkmcnt(0)
	s_cbranch_scc1 .LBB0_687

; __device__ __forceinline__ void convert_layer(PP P, int l, LAS unsigned char* lds, const Ids I) {
;     ...
;     for (int u = BID; u < 7 * 176 + 64; u += NB) {
;         const int mi = u / 176, uu = u - mi * 176;
;         if (mi == 0)      conv_tile4(P->in[I_F1G] + wl, 1024, 2816, (bf16_t*)(ws + WS_WGU1), 5, uu, T, I);
;         else if (mi == 1) conv_tile4(P->in[I_F1U] + wl, 1024, 2816, (bf16_t*)(ws + WS_WGU1), 6, uu, T, I);
;         else if (mi == 2) conv_tile4(P->in[I_F1D] + wl, 2816, 1024, (bf16_t*)(ws + WS_WD1), 0, uu, T, I);
;         else if (mi == 3) conv_tile4(P->in[I_WIN] + wl, 1024, 2816, (bf16_t*)(ws + WS_WIN), 4, uu, T, I);
;         else if (mi == 4) conv_tile4(P->in[I_F2G] + wl, 1024, 2816, (bf16_t*)(ws + WS_WGU2), 5, uu, T, I);
;         else if (mi == 5) conv_tile4(P->in[I_F2U] + wl, 1024, 2816, (bf16_t*)(ws + WS_WGU2), 6, uu, T, I);
;         else if (mi == 6) conv_tile4(P->in[I_F2D] + wl, 2816, 1024, (bf16_t*)(ws + WS_WD2), 0, uu, T, I);
;         else              conv_tile4(P->in[I_WOUT] + (size_t)l * 1024 * 1024, 1024, 1024, (bf16_t*)(ws + WS_WOUT), 0, uu, T, I);
;     }
; __global__ void __launch_bounds__(512) mega(Params Pval) {
;     ...
;             if (I.nb > 144) { if (I.bid < 72) { EpiAda E{(float*)(ws + WS_MOD), P->in[I_BADA]}; run_gemm(lds, (const bf16_t*)(ws + WS_AADA), (const bf16_t*)(ws + WS_R2), 256, 2 * 9216, 1024, E, I); }
;                               else { Ids J = I; J.bid = I.bid - 72; J.nb = I.nb - 72; convert_layer(P, 0, lds, J); } }
.LBB0_715:
	s_barrier
	s_cmp_gt_u32 s93, 7
	s_cbranch_scc1 .LBB0_716
	s_add_i32 s16, s93, 0x508
	s_movk_i32 s17, 0x1000
	s_add_i32 s18, s93, 0xe8
	s_add_u32 s48, s86, 0x4000
	s_addc_u32 s49, s87, 0
	s_branch .LBB0_659
